# top-k compaction: wave min/max of the order keys by DPP row_shr + readlane instead of six ds_bpermute round trips (size-preserving padding keeps downstream code addresses)
# baseline (speedup 1.0000x reference)
; #define LDS_WAIT() asm volatile("s_waitcnt lgkmcnt(0)" ::: "memory")
; __device__ __forceinline__ int lane_id() { int l; asm volatile("v_mbcnt_lo_u32_b32 %0, -1, 0\n\tv_mbcnt_hi_u32_b32 %0, -1, %0\n\ts_nop 1" : "=v"(l)); return l; }
; __device__ __forceinline__ unsigned f2ord(float f) { const unsigned u = __float_as_uint(f); return u ^ ((u >> 31) ? 0xFFFFFFFFu : 0x80000000u); }
; __device__ __forceinline__ int topk_compact(LAS u32x2* buf, int cnt, float& tau) {
;     const int lane = lane_id();
;     LDS_WAIT();
;     unsigned key[12], idx[12];
;     unsigned kmin = 0xFFFFFFFFu, kmax = 0u;
; #pragma unroll
;     for (int j = 0; j < 12; ++j) { const int e = j * 64 + lane; const u32x2 v = buf[e]; const bool ok = e < cnt; const unsigned k = f2ord(__uint_as_float(v.x)); key[j] = ok ? k : 0u; idx[j] = v.y;
;         kmin = (ok && k < kmin) ? k : kmin; kmax = (ok && k > kmax) ? k : kmax; }
; #pragma unroll
;     for (int o = 1; o < 64; o <<= 1) { const unsigned a = (unsigned)__shfl_xor((int)kmin, o), b = (unsigned)__shfl_xor((int)kmax, o); kmin = a < kmin ? a : kmin; kmax = b > kmax ? b : kmax; }
;     const unsigned diff = (unsigned)__builtin_amdgcn_readfirstlane((int)(kmin ^ kmax));
;     int bit = diff ? (31 - __builtin_clz(diff)) : -1;
;     unsigned T = (bit >= 0) ? (unsigned)__builtin_amdgcn_readfirstlane((int)kmin) & ~((2u << bit) - 1u) : (unsigned)__builtin_amdgcn_readfirstlane((int)kmin);
.Lidx_compact:
	s_cmpk_lt_i32 s74, 0x101
	s_cbranch_scc1 .LBB0_485
	v_mbcnt_lo_u32_b32 v25, -1, 0
	v_mbcnt_hi_u32_b32 v25, -1, v25
	s_nop 1
	s_waitcnt lgkmcnt(0)
	s_nop 0
	v_lshl_add_u32 v0, v25, 3, s97
	ds_read2st64_b64 v[20:23], v0 offset1:1
	ds_read2st64_b64 v[8:11], v0 offset0:2 offset1:3
	v_add_u32_e32 v2, 64, v25
	v_cmp_gt_i32_e64 s[12:13], s74, v2
	ds_read2st64_b64 v[16:19], v0 offset0:4 offset1:5
	ds_read2st64_b64 v[12:15], v0 offset0:6 offset1:7
	s_waitcnt lgkmcnt(3)
	v_cmp_lt_i32_e32 vcc, -1, v20
	v_add_u32_e32 v27, 0x200, v25
	v_cmp_gt_i32_e64 s[26:27], s74, v27
	v_cndmask_b32_e32 v1, -1, v123, vcc
	v_xor_b32_e32 v1, v1, v20
	v_cmp_gt_i32_e32 vcc, s74, v25
	s_nop 1
	v_cndmask_b32_e32 v24, 0, v1, vcc
	v_cndmask_b32_e32 v1, -1, v1, vcc
	v_cmp_lt_i32_e32 vcc, -1, v22
	s_nop 1
	v_cndmask_b32_e32 v3, -1, v123, vcc
	v_xor_b32_e32 v20, v3, v22
	s_waitcnt lgkmcnt(2)
	v_cmp_lt_i32_e32 vcc, -1, v8
	v_min_u32_e32 v3, v20, v1
	v_cndmask_b32_e64 v1, v1, v3, s[12:13]
	v_cndmask_b32_e32 v4, -1, v123, vcc
	v_max_u32_e32 v2, v20, v24
	v_add_u32_e32 v3, 0x80, v25
	v_xor_b32_e32 v8, v4, v8
	v_cndmask_b32_e64 v2, v24, v2, s[12:13]
	v_min_u32_e32 v4, v8, v1
	v_cmp_gt_i32_e64 s[14:15], s74, v3
	v_cmp_lt_i32_e32 vcc, -1, v10
	v_max_u32_e32 v3, v8, v2
	v_cndmask_b32_e64 v1, v1, v4, s[14:15]
	v_cndmask_b32_e32 v4, -1, v123, vcc
	v_cndmask_b32_e64 v2, v2, v3, s[14:15]
	v_add_u32_e32 v3, 0xc0, v25
	v_xor_b32_e32 v10, v4, v10
	v_min_u32_e32 v4, v10, v1
	v_cmp_gt_i32_e64 s[16:17], s74, v3
	s_waitcnt lgkmcnt(1)
	v_cmp_lt_i32_e32 vcc, -1, v16
	v_max_u32_e32 v3, v10, v2
	v_cndmask_b32_e64 v1, v1, v4, s[16:17]
	v_cndmask_b32_e32 v4, -1, v123, vcc
	v_cndmask_b32_e64 v2, v2, v3, s[16:17]
	v_add_u32_e32 v3, 0x100, v25
	v_xor_b32_e32 v16, v4, v16
	v_min_u32_e32 v4, v16, v1
	v_cmp_gt_i32_e64 s[18:19], s74, v3
	v_cmp_lt_i32_e32 vcc, -1, v18
	v_max_u32_e32 v3, v16, v2
	v_cndmask_b32_e64 v1, v1, v4, s[18:19]
	v_cndmask_b32_e32 v4, -1, v123, vcc
	v_cndmask_b32_e64 v2, v2, v3, s[18:19]
	v_add_u32_e32 v3, 0x140, v25
	v_xor_b32_e32 v18, v4, v18
	v_min_u32_e32 v4, v18, v1
	v_cmp_gt_i32_e64 s[20:21], s74, v3
	s_waitcnt lgkmcnt(0)
	v_cmp_lt_i32_e32 vcc, -1, v12
	v_max_u32_e32 v3, v18, v2
	v_cndmask_b32_e64 v1, v1, v4, s[20:21]
	v_cndmask_b32_e32 v4, -1, v123, vcc
	v_cndmask_b32_e64 v2, v2, v3, s[20:21]
	v_add_u32_e32 v3, 0x180, v25
	v_xor_b32_e32 v12, v4, v12
	v_min_u32_e32 v4, v12, v1
	v_cmp_gt_i32_e64 s[22:23], s74, v3
	v_cmp_lt_i32_e32 vcc, -1, v14
	v_max_u32_e32 v3, v12, v2
	v_cndmask_b32_e64 v1, v1, v4, s[22:23]
	v_cndmask_b32_e32 v4, -1, v123, vcc
	v_cndmask_b32_e64 v2, v2, v3, s[22:23]
	v_add_u32_e32 v3, 0x1c0, v25
	v_xor_b32_e32 v14, v4, v14
	v_min_u32_e32 v4, v14, v1
	v_cmp_gt_i32_e64 s[24:25], s74, v3
	s_nop 1
	v_cndmask_b32_e64 v22, v1, v4, s[24:25]
	ds_read2st64_b64 v[4:7], v0 offset0:8 offset1:9
	v_max_u32_e32 v1, v14, v2
	v_cndmask_b32_e64 v26, v2, v1, s[24:25]
	ds_read2st64_b64 v[0:3], v0 offset0:10 offset1:11
	s_waitcnt lgkmcnt(1)
	v_cmp_lt_i32_e32 vcc, -1, v4
	s_nop 1
	v_cndmask_b32_e32 v28, -1, v123, vcc
	v_xor_b32_e32 v4, v28, v4
	v_min_u32_e32 v28, v4, v22
	v_cmp_lt_i32_e32 vcc, -1, v6
	v_cndmask_b32_e64 v22, v22, v28, s[26:27]
	v_max_u32_e32 v27, v4, v26
	v_cndmask_b32_e32 v28, -1, v123, vcc
	v_cndmask_b32_e64 v26, v26, v27, s[26:27]
	v_add_u32_e32 v27, 0x240, v25
	v_xor_b32_e32 v6, v28, v6
	v_min_u32_e32 v28, v6, v22
	v_cmp_gt_i32_e64 s[28:29], s74, v27
	s_waitcnt lgkmcnt(0)
	v_cmp_lt_i32_e32 vcc, -1, v0
	v_max_u32_e32 v27, v6, v26
	v_cndmask_b32_e64 v22, v22, v28, s[28:29]
	v_cndmask_b32_e32 v28, -1, v123, vcc
	v_cndmask_b32_e64 v26, v26, v27, s[28:29]
	v_add_u32_e32 v27, 0x280, v25
	v_xor_b32_e32 v0, v28, v0
	v_cmp_gt_i32_e64 s[30:31], s74, v27
	v_max_u32_e32 v27, v0, v26
	v_cmp_lt_i32_e32 vcc, -1, v2
	v_cndmask_b32_e64 v26, v26, v27, s[30:31]
	v_min_u32_e32 v28, v0, v22
	v_cndmask_b32_e32 v27, -1, v123, vcc
	v_add_u32_e32 v25, 0x2c0, v25
	v_xor_b32_e32 v2, v27, v2
	v_cndmask_b32_e64 v22, v22, v28, s[30:31]
	v_cmp_gt_i32_e64 s[34:35], s74, v25
	v_max_u32_e32 v25, v2, v26
	v_min_u32_e32 v27, v2, v22
	v_cndmask_b32_e64 v25, v26, v25, s[34:35]
	v_and_b32_e32 v26, 64, v144
	v_cndmask_b32_e64 v22, v22, v27, s[34:35]
	v_add_u32_e32 v26, 64, v26
	s_nop 1
	v_min_u32_dpp v22, v22, v22 row_shr:1 row_mask:0xf bank_mask:0xf
	v_max_u32_dpp v25, v25, v25 row_shr:1 row_mask:0xf bank_mask:0xf
	s_nop 0
	v_min_u32_dpp v22, v22, v22 row_shr:2 row_mask:0xf bank_mask:0xf
	v_max_u32_dpp v25, v25, v25 row_shr:2 row_mask:0xf bank_mask:0xf
	s_nop 0
	v_min_u32_dpp v22, v22, v22 row_shr:4 row_mask:0xf bank_mask:0xf
	v_max_u32_dpp v25, v25, v25 row_shr:4 row_mask:0xf bank_mask:0xf
	s_nop 0
	v_min_u32_dpp v22, v22, v22 row_shr:8 row_mask:0xf bank_mask:0xf
	v_max_u32_dpp v25, v25, v25 row_shr:8 row_mask:0xf bank_mask:0xf
	s_nop 0
	v_readlane_b32 s4, v22, 15
	v_readlane_b32 s5, v22, 31
	s_min_u32 s4, s4, s5
	v_readlane_b32 s5, v22, 47
	s_min_u32 s4, s4, s5
	v_readlane_b32 s5, v22, 63
	s_min_u32 s4, s4, s5
	v_mov_b32_e32 v22, s4
	v_readlane_b32 s4, v25, 15
	v_readlane_b32 s5, v25, 31
	s_max_u32 s4, s4, s5
	v_readlane_b32 s5, v25, 47
	s_max_u32 s4, s4, s5
	v_readlane_b32 s5, v25, 63
	s_max_u32 s4, s4, s5
	v_mov_b32_e32 v25, s4
	s_branch .Lpad_kmm5749
	s_nop 0
	s_nop 0
	s_nop 0
	s_nop 0
	s_nop 0
	s_nop 0
	s_nop 0
	s_nop 0
	s_nop 0
	s_nop 0
	s_nop 0
	s_nop 0
	s_nop 0
	s_nop 0
	s_nop 0
	s_nop 0
	s_nop 0
	s_nop 0
	s_nop 0
	s_nop 0
	s_nop 0
	s_nop 0
	s_nop 0
	s_nop 0
	s_nop 0
	s_nop 0
	s_nop 0
	s_nop 0
	s_nop 0
	s_nop 0
	s_nop 0
	s_nop 0
.Lpad_kmm5749:
	v_xor_b32_e32 v25, v22, v25
	s_nop 0
	v_readfirstlane_b32 s5, v25
	s_cmp_lg_u32 s5, 0
	s_flbit_i32_b32 s4, s5
	s_cselect_b64 s[36:37], -1, 0
	s_xor_b32 s4, s4, 31
	s_cmp_eq_u32 s5, 0
	s_cbranch_scc1 .LBB0_456
	v_readfirstlane_b32 s5, v22
	s_lshl_b32 s94, -2, s4
	s_and_b32 s5, s5, s94
	s_cbranch_execnz .LBB0_395

; #define LDS_WAIT() asm volatile("s_waitcnt lgkmcnt(0)" ::: "memory")
; __device__ __forceinline__ int lane_id() { int l; asm volatile("v_mbcnt_lo_u32_b32 %0, -1, 0\n\tv_mbcnt_hi_u32_b32 %0, -1, %0\n\ts_nop 1" : "=v"(l)); return l; }
; __device__ __forceinline__ unsigned f2ord(float f) { const unsigned u = __float_as_uint(f); return u ^ ((u >> 31) ? 0xFFFFFFFFu : 0x80000000u); }
; __device__ __forceinline__ int topk_compact(LAS u32x2* buf, int cnt, float& tau) {
;     const int lane = lane_id();
;     LDS_WAIT();
;     unsigned key[12], idx[12];
;     unsigned kmin = 0xFFFFFFFFu, kmax = 0u;
; #pragma unroll
;     for (int j = 0; j < 12; ++j) { const int e = j * 64 + lane; const u32x2 v = buf[e]; const bool ok = e < cnt; const unsigned k = f2ord(__uint_as_float(v.x)); key[j] = ok ? k : 0u; idx[j] = v.y;
;         kmin = (ok && k < kmin) ? k : kmin; kmax = (ok && k > kmax) ? k : kmax; }
; #pragma unroll
;     for (int o = 1; o < 64; o <<= 1) { const unsigned a = (unsigned)__shfl_xor((int)kmin, o), b = (unsigned)__shfl_xor((int)kmax, o); kmin = a < kmin ? a : kmin; kmax = b > kmax ? b : kmax; }
;     const unsigned diff = (unsigned)__builtin_amdgcn_readfirstlane((int)(kmin ^ kmax));
;     int bit = diff ? (31 - __builtin_clz(diff)) : -1;
;     unsigned T = (bit >= 0) ? (unsigned)__builtin_amdgcn_readfirstlane((int)kmin) & ~((2u << bit) - 1u) : (unsigned)__builtin_amdgcn_readfirstlane((int)kmin);
.LBB0_485:
	s_cmpk_lt_i32 s75, 0x101
	s_cbranch_scc1 .LBB0_571
	v_mbcnt_lo_u32_b32 v25, -1, 0
	v_mbcnt_hi_u32_b32 v25, -1, v25
	s_nop 1
	s_waitcnt lgkmcnt(0)
	s_nop 0
	v_lshl_add_u32 v0, v25, 3, s97
	ds_read2st64_b64 v[20:23], v0 offset0:12 offset1:13
	ds_read2st64_b64 v[8:11], v0 offset0:14 offset1:15
	v_add_u32_e32 v2, 64, v25
	v_cmp_gt_i32_e64 s[12:13], s75, v2
	ds_read2st64_b64 v[16:19], v0 offset0:16 offset1:17
	ds_read2st64_b64 v[12:15], v0 offset0:18 offset1:19
	s_waitcnt lgkmcnt(3)
	v_cmp_lt_i32_e32 vcc, -1, v20
	v_add_u32_e32 v27, 0x200, v25
	v_cmp_gt_i32_e64 s[26:27], s75, v27
	v_cndmask_b32_e32 v1, -1, v123, vcc
	v_xor_b32_e32 v1, v1, v20
	v_cmp_gt_i32_e32 vcc, s75, v25
	s_nop 1
	v_cndmask_b32_e32 v24, 0, v1, vcc
	v_cndmask_b32_e32 v1, -1, v1, vcc
	v_cmp_lt_i32_e32 vcc, -1, v22
	s_nop 1
	v_cndmask_b32_e32 v3, -1, v123, vcc
	v_xor_b32_e32 v20, v3, v22
	s_waitcnt lgkmcnt(2)
	v_cmp_lt_i32_e32 vcc, -1, v8
	v_min_u32_e32 v3, v20, v1
	v_cndmask_b32_e64 v1, v1, v3, s[12:13]
	v_cndmask_b32_e32 v4, -1, v123, vcc
	v_max_u32_e32 v2, v20, v24
	v_add_u32_e32 v3, 0x80, v25
	v_xor_b32_e32 v8, v4, v8
	v_cndmask_b32_e64 v2, v24, v2, s[12:13]
	v_min_u32_e32 v4, v8, v1
	v_cmp_gt_i32_e64 s[14:15], s75, v3
	v_cmp_lt_i32_e32 vcc, -1, v10
	v_max_u32_e32 v3, v8, v2
	v_cndmask_b32_e64 v1, v1, v4, s[14:15]
	v_cndmask_b32_e32 v4, -1, v123, vcc
	v_cndmask_b32_e64 v2, v2, v3, s[14:15]
	v_add_u32_e32 v3, 0xc0, v25
	v_xor_b32_e32 v10, v4, v10
	v_min_u32_e32 v4, v10, v1
	v_cmp_gt_i32_e64 s[16:17], s75, v3
	s_waitcnt lgkmcnt(1)
	v_cmp_lt_i32_e32 vcc, -1, v16
	v_max_u32_e32 v3, v10, v2
	v_cndmask_b32_e64 v1, v1, v4, s[16:17]
	v_cndmask_b32_e32 v4, -1, v123, vcc
	v_cndmask_b32_e64 v2, v2, v3, s[16:17]
	v_add_u32_e32 v3, 0x100, v25
	v_xor_b32_e32 v16, v4, v16
	v_min_u32_e32 v4, v16, v1
	v_cmp_gt_i32_e64 s[18:19], s75, v3
	v_cmp_lt_i32_e32 vcc, -1, v18
	v_max_u32_e32 v3, v16, v2
	v_cndmask_b32_e64 v1, v1, v4, s[18:19]
	v_cndmask_b32_e32 v4, -1, v123, vcc
	v_cndmask_b32_e64 v2, v2, v3, s[18:19]
	v_add_u32_e32 v3, 0x140, v25
	v_xor_b32_e32 v18, v4, v18
	v_min_u32_e32 v4, v18, v1
	v_cmp_gt_i32_e64 s[20:21], s75, v3
	s_waitcnt lgkmcnt(0)
	v_cmp_lt_i32_e32 vcc, -1, v12
	v_max_u32_e32 v3, v18, v2
	v_cndmask_b32_e64 v1, v1, v4, s[20:21]
	v_cndmask_b32_e32 v4, -1, v123, vcc
	v_cndmask_b32_e64 v2, v2, v3, s[20:21]
	v_add_u32_e32 v3, 0x180, v25
	v_xor_b32_e32 v12, v4, v12
	v_min_u32_e32 v4, v12, v1
	v_cmp_gt_i32_e64 s[22:23], s75, v3
	v_cmp_lt_i32_e32 vcc, -1, v14
	v_max_u32_e32 v3, v12, v2
	v_cndmask_b32_e64 v1, v1, v4, s[22:23]
	v_cndmask_b32_e32 v4, -1, v123, vcc
	v_cndmask_b32_e64 v2, v2, v3, s[22:23]
	v_add_u32_e32 v3, 0x1c0, v25
	v_xor_b32_e32 v14, v4, v14
	v_min_u32_e32 v4, v14, v1
	v_cmp_gt_i32_e64 s[24:25], s75, v3
	s_nop 1
	v_cndmask_b32_e64 v22, v1, v4, s[24:25]
	ds_read2st64_b64 v[4:7], v0 offset0:20 offset1:21
	v_max_u32_e32 v1, v14, v2
	v_cndmask_b32_e64 v26, v2, v1, s[24:25]
	ds_read2st64_b64 v[0:3], v0 offset0:22 offset1:23
	s_waitcnt lgkmcnt(1)
	v_cmp_lt_i32_e32 vcc, -1, v4
	s_nop 1
	v_cndmask_b32_e32 v28, -1, v123, vcc
	v_xor_b32_e32 v4, v28, v4
	v_min_u32_e32 v28, v4, v22
	v_cmp_lt_i32_e32 vcc, -1, v6
	v_cndmask_b32_e64 v22, v22, v28, s[26:27]
	v_max_u32_e32 v27, v4, v26
	v_cndmask_b32_e32 v28, -1, v123, vcc
	v_cndmask_b32_e64 v26, v26, v27, s[26:27]
	v_add_u32_e32 v27, 0x240, v25
	v_xor_b32_e32 v6, v28, v6
	v_min_u32_e32 v28, v6, v22
	v_cmp_gt_i32_e64 s[28:29], s75, v27
	s_waitcnt lgkmcnt(0)
	v_cmp_lt_i32_e32 vcc, -1, v0
	v_max_u32_e32 v27, v6, v26
	v_cndmask_b32_e64 v22, v22, v28, s[28:29]
	v_cndmask_b32_e32 v28, -1, v123, vcc
	v_cndmask_b32_e64 v26, v26, v27, s[28:29]
	v_add_u32_e32 v27, 0x280, v25
	v_xor_b32_e32 v0, v28, v0
	v_cmp_gt_i32_e64 s[30:31], s75, v27
	v_max_u32_e32 v27, v0, v26
	v_cmp_lt_i32_e32 vcc, -1, v2
	v_cndmask_b32_e64 v26, v26, v27, s[30:31]
	v_min_u32_e32 v28, v0, v22
	v_cndmask_b32_e32 v27, -1, v123, vcc
	v_add_u32_e32 v25, 0x2c0, v25
	v_xor_b32_e32 v2, v27, v2
	v_cndmask_b32_e64 v22, v22, v28, s[30:31]
	v_cmp_gt_i32_e64 s[34:35], s75, v25
	v_max_u32_e32 v25, v2, v26
	v_min_u32_e32 v27, v2, v22
	v_cndmask_b32_e64 v25, v26, v25, s[34:35]
	v_and_b32_e32 v26, 64, v144
	v_cndmask_b32_e64 v22, v22, v27, s[34:35]
	v_add_u32_e32 v26, 64, v26
	s_nop 1
	v_min_u32_dpp v22, v22, v22 row_shr:1 row_mask:0xf bank_mask:0xf
	v_max_u32_dpp v25, v25, v25 row_shr:1 row_mask:0xf bank_mask:0xf
	s_nop 0
	v_min_u32_dpp v22, v22, v22 row_shr:2 row_mask:0xf bank_mask:0xf
	v_max_u32_dpp v25, v25, v25 row_shr:2 row_mask:0xf bank_mask:0xf
	s_nop 0
	v_min_u32_dpp v22, v22, v22 row_shr:4 row_mask:0xf bank_mask:0xf
	v_max_u32_dpp v25, v25, v25 row_shr:4 row_mask:0xf bank_mask:0xf
	s_nop 0
	v_min_u32_dpp v22, v22, v22 row_shr:8 row_mask:0xf bank_mask:0xf
	v_max_u32_dpp v25, v25, v25 row_shr:8 row_mask:0xf bank_mask:0xf
	s_nop 0
	v_readlane_b32 s4, v22, 15
	v_readlane_b32 s5, v22, 31
	s_min_u32 s4, s4, s5
	v_readlane_b32 s5, v22, 47
	s_min_u32 s4, s4, s5
	v_readlane_b32 s5, v22, 63
	s_min_u32 s4, s4, s5
	v_mov_b32_e32 v22, s4
	v_readlane_b32 s4, v25, 15
	v_readlane_b32 s5, v25, 31
	s_max_u32 s4, s4, s5
	v_readlane_b32 s5, v25, 47
	s_max_u32 s4, s4, s5
	v_readlane_b32 s5, v25, 63
	s_max_u32 s4, s4, s5
	v_mov_b32_e32 v25, s4
	s_branch .Lpad_kmm6748
	s_nop 0
	s_nop 0
	s_nop 0
	s_nop 0
	s_nop 0
	s_nop 0
	s_nop 0
	s_nop 0
	s_nop 0
	s_nop 0
	s_nop 0
	s_nop 0
	s_nop 0
	s_nop 0
	s_nop 0
	s_nop 0
	s_nop 0
	s_nop 0
	s_nop 0
	s_nop 0
	s_nop 0
	s_nop 0
	s_nop 0
	s_nop 0
	s_nop 0
	s_nop 0
	s_nop 0
	s_nop 0
	s_nop 0
	s_nop 0
	s_nop 0
	s_nop 0

; #define LDS_WAIT() asm volatile("s_waitcnt lgkmcnt(0)" ::: "memory")
; __device__ __forceinline__ int lane_id() { int l; asm volatile("v_mbcnt_lo_u32_b32 %0, -1, 0\n\tv_mbcnt_hi_u32_b32 %0, -1, %0\n\ts_nop 1" : "=v"(l)); return l; }
; __device__ __forceinline__ unsigned f2ord(float f) { const unsigned u = __float_as_uint(f); return u ^ ((u >> 31) ? 0xFFFFFFFFu : 0x80000000u); }
; __device__ __forceinline__ int topk_compact(LAS u32x2* buf, int cnt, float& tau) {
;     const int lane = lane_id();
;     LDS_WAIT();
;     unsigned key[12], idx[12];
;     unsigned kmin = 0xFFFFFFFFu, kmax = 0u;
; #pragma unroll
;     for (int j = 0; j < 12; ++j) { const int e = j * 64 + lane; const u32x2 v = buf[e]; const bool ok = e < cnt; const unsigned k = f2ord(__uint_as_float(v.x)); key[j] = ok ? k : 0u; idx[j] = v.y;
;         kmin = (ok && k < kmin) ? k : kmin; kmax = (ok && k > kmax) ? k : kmax; }
; #pragma unroll
;     for (int o = 1; o < 64; o <<= 1) { const unsigned a = (unsigned)__shfl_xor((int)kmin, o), b = (unsigned)__shfl_xor((int)kmax, o); kmin = a < kmin ? a : kmin; kmax = b > kmax ? b : kmax; }
;     const unsigned diff = (unsigned)__builtin_amdgcn_readfirstlane((int)(kmin ^ kmax));
;     int bit = diff ? (31 - __builtin_clz(diff)) : -1;
;     unsigned T = (bit >= 0) ? (unsigned)__builtin_amdgcn_readfirstlane((int)kmin) & ~((2u << bit) - 1u) : (unsigned)__builtin_amdgcn_readfirstlane((int)kmin);
.LBB0_573:
	s_cmpk_gt_i32 s74, 0x100
	s_cbranch_scc0 .LBB0_659
	v_mbcnt_lo_u32_b32 v25, -1, 0
	v_mbcnt_hi_u32_b32 v25, -1, v25
	s_nop 1
	s_waitcnt lgkmcnt(0)
	s_waitcnt vmcnt(0)
	v_lshl_add_u32 v0, v25, 3, s97
	ds_read2st64_b64 v[20:23], v0 offset1:1
	ds_read2st64_b64 v[8:11], v0 offset0:2 offset1:3
	v_add_u32_e32 v2, 64, v25
	v_cmp_gt_i32_e64 s[6:7], s74, v2
	ds_read2st64_b64 v[16:19], v0 offset0:4 offset1:5
	ds_read2st64_b64 v[12:15], v0 offset0:6 offset1:7
	s_waitcnt lgkmcnt(3)
	v_cmp_lt_i32_e32 vcc, -1, v20
	v_add_u32_e32 v27, 0x200, v25
	v_cmp_gt_i32_e64 s[20:21], s74, v27
	v_cndmask_b32_e32 v1, -1, v123, vcc
	v_xor_b32_e32 v1, v1, v20
	v_cmp_gt_i32_e32 vcc, s74, v25
	s_nop 1
	v_cndmask_b32_e32 v24, 0, v1, vcc
	v_cndmask_b32_e32 v1, -1, v1, vcc
	v_cmp_lt_i32_e32 vcc, -1, v22
	s_nop 1
	v_cndmask_b32_e32 v3, -1, v123, vcc
	v_xor_b32_e32 v20, v3, v22
	s_waitcnt lgkmcnt(2)
	v_cmp_lt_i32_e32 vcc, -1, v8
	v_min_u32_e32 v3, v20, v1
	v_cndmask_b32_e64 v1, v1, v3, s[6:7]
	v_cndmask_b32_e32 v4, -1, v123, vcc
	v_max_u32_e32 v2, v20, v24
	v_add_u32_e32 v3, 0x80, v25
	v_xor_b32_e32 v8, v4, v8
	v_cndmask_b32_e64 v2, v24, v2, s[6:7]
	v_min_u32_e32 v4, v8, v1
	v_cmp_gt_i32_e64 s[8:9], s74, v3
	v_cmp_lt_i32_e32 vcc, -1, v10
	v_max_u32_e32 v3, v8, v2
	v_cndmask_b32_e64 v1, v1, v4, s[8:9]
	v_cndmask_b32_e32 v4, -1, v123, vcc
	v_cndmask_b32_e64 v2, v2, v3, s[8:9]
	v_add_u32_e32 v3, 0xc0, v25
	v_xor_b32_e32 v10, v4, v10
	v_min_u32_e32 v4, v10, v1
	v_cmp_gt_i32_e64 s[10:11], s74, v3
	s_waitcnt lgkmcnt(1)
	v_cmp_lt_i32_e32 vcc, -1, v16
	v_max_u32_e32 v3, v10, v2
	v_cndmask_b32_e64 v1, v1, v4, s[10:11]
	v_cndmask_b32_e32 v4, -1, v123, vcc
	v_cndmask_b32_e64 v2, v2, v3, s[10:11]
	v_add_u32_e32 v3, 0x100, v25
	v_xor_b32_e32 v16, v4, v16
	v_min_u32_e32 v4, v16, v1
	v_cmp_gt_i32_e64 s[12:13], s74, v3
	v_cmp_lt_i32_e32 vcc, -1, v18
	v_max_u32_e32 v3, v16, v2
	v_cndmask_b32_e64 v1, v1, v4, s[12:13]
	v_cndmask_b32_e32 v4, -1, v123, vcc
	v_cndmask_b32_e64 v2, v2, v3, s[12:13]
	v_add_u32_e32 v3, 0x140, v25
	v_xor_b32_e32 v18, v4, v18
	v_min_u32_e32 v4, v18, v1
	v_cmp_gt_i32_e64 s[14:15], s74, v3
	s_waitcnt lgkmcnt(0)
	v_cmp_lt_i32_e32 vcc, -1, v12
	v_max_u32_e32 v3, v18, v2
	v_cndmask_b32_e64 v1, v1, v4, s[14:15]
	v_cndmask_b32_e32 v4, -1, v123, vcc
	v_cndmask_b32_e64 v2, v2, v3, s[14:15]
	v_add_u32_e32 v3, 0x180, v25
	v_xor_b32_e32 v12, v4, v12
	v_min_u32_e32 v4, v12, v1
	v_cmp_gt_i32_e64 s[16:17], s74, v3
	v_cmp_lt_i32_e32 vcc, -1, v14
	v_max_u32_e32 v3, v12, v2
	v_cndmask_b32_e64 v1, v1, v4, s[16:17]
	v_cndmask_b32_e32 v4, -1, v123, vcc
	v_cndmask_b32_e64 v2, v2, v3, s[16:17]
	v_add_u32_e32 v3, 0x1c0, v25
	v_xor_b32_e32 v14, v4, v14
	v_min_u32_e32 v4, v14, v1
	v_cmp_gt_i32_e64 s[18:19], s74, v3
	s_nop 1
	v_cndmask_b32_e64 v22, v1, v4, s[18:19]
	ds_read2st64_b64 v[4:7], v0 offset0:8 offset1:9
	v_max_u32_e32 v1, v14, v2
	v_cndmask_b32_e64 v26, v2, v1, s[18:19]
	ds_read2st64_b64 v[0:3], v0 offset0:10 offset1:11
	s_waitcnt lgkmcnt(1)
	v_cmp_lt_i32_e32 vcc, -1, v4
	s_nop 1
	v_cndmask_b32_e32 v28, -1, v123, vcc
	v_xor_b32_e32 v4, v28, v4
	v_min_u32_e32 v28, v4, v22
	v_cmp_lt_i32_e32 vcc, -1, v6
	v_cndmask_b32_e64 v22, v22, v28, s[20:21]
	v_max_u32_e32 v27, v4, v26
	v_cndmask_b32_e32 v28, -1, v123, vcc
	v_cndmask_b32_e64 v26, v26, v27, s[20:21]
	v_add_u32_e32 v27, 0x240, v25
	v_xor_b32_e32 v6, v28, v6
	v_min_u32_e32 v28, v6, v22
	v_cmp_gt_i32_e64 s[22:23], s74, v27
	s_waitcnt lgkmcnt(0)
	v_cmp_lt_i32_e32 vcc, -1, v0
	v_max_u32_e32 v27, v6, v26
	v_cndmask_b32_e64 v22, v22, v28, s[22:23]
	v_cndmask_b32_e32 v28, -1, v123, vcc
	v_cndmask_b32_e64 v26, v26, v27, s[22:23]
	v_add_u32_e32 v27, 0x280, v25
	v_xor_b32_e32 v0, v28, v0
	v_cmp_gt_i32_e64 s[24:25], s74, v27
	v_max_u32_e32 v27, v0, v26
	v_cmp_lt_i32_e32 vcc, -1, v2
	v_cndmask_b32_e64 v26, v26, v27, s[24:25]
	v_min_u32_e32 v28, v0, v22
	v_cndmask_b32_e32 v27, -1, v123, vcc
	v_add_u32_e32 v25, 0x2c0, v25
	v_xor_b32_e32 v2, v27, v2
	v_cndmask_b32_e64 v22, v22, v28, s[24:25]
	v_cmp_gt_i32_e64 s[26:27], s74, v25
	v_max_u32_e32 v25, v2, v26
	v_min_u32_e32 v27, v2, v22
	v_cndmask_b32_e64 v25, v26, v25, s[26:27]
	v_and_b32_e32 v26, 64, v144
	v_cndmask_b32_e64 v22, v22, v27, s[26:27]
	v_add_u32_e32 v26, 64, v26
	s_nop 1
	v_min_u32_dpp v22, v22, v22 row_shr:1 row_mask:0xf bank_mask:0xf
	v_max_u32_dpp v25, v25, v25 row_shr:1 row_mask:0xf bank_mask:0xf
	s_nop 0
	v_min_u32_dpp v22, v22, v22 row_shr:2 row_mask:0xf bank_mask:0xf
	v_max_u32_dpp v25, v25, v25 row_shr:2 row_mask:0xf bank_mask:0xf
	s_nop 0
	v_min_u32_dpp v22, v22, v22 row_shr:4 row_mask:0xf bank_mask:0xf
	v_max_u32_dpp v25, v25, v25 row_shr:4 row_mask:0xf bank_mask:0xf
	s_nop 0
	v_min_u32_dpp v22, v22, v22 row_shr:8 row_mask:0xf bank_mask:0xf
	v_max_u32_dpp v25, v25, v25 row_shr:8 row_mask:0xf bank_mask:0xf
	s_nop 0
	v_readlane_b32 s4, v22, 15
	v_readlane_b32 s5, v22, 31
	s_min_u32 s4, s4, s5
	v_readlane_b32 s5, v22, 47
	s_min_u32 s4, s4, s5
	v_readlane_b32 s5, v22, 63
	s_min_u32 s4, s4, s5
	v_mov_b32_e32 v22, s4
	v_readlane_b32 s4, v25, 15
	v_readlane_b32 s5, v25, 31
	s_max_u32 s4, s4, s5
	v_readlane_b32 s5, v25, 47
	s_max_u32 s4, s4, s5
	v_readlane_b32 s5, v25, 63
	s_max_u32 s4, s4, s5
	v_mov_b32_e32 v25, s4
	s_branch .Lpad_kmm7705
	s_nop 0
	s_nop 0
	s_nop 0
	s_nop 0
	s_nop 0
	s_nop 0
	s_nop 0
	s_nop 0
	s_nop 0
	s_nop 0
	s_nop 0
	s_nop 0
	s_nop 0
	s_nop 0
	s_nop 0
	s_nop 0
	s_nop 0
	s_nop 0
	s_nop 0
	s_nop 0
	s_nop 0
	s_nop 0
	s_nop 0
	s_nop 0
	s_nop 0
	s_nop 0
	s_nop 0
	s_nop 0
	s_nop 0
	s_nop 0
	s_nop 0
	s_nop 0
.Lpad_kmm7705:
	v_xor_b32_e32 v25, v22, v25
	s_nop 0
	v_readfirstlane_b32 s5, v25
	s_cmp_lg_u32 s5, 0
	s_flbit_i32_b32 s4, s5
	s_cselect_b64 s[28:29], -1, 0
	s_xor_b32 s4, s4, 31
	s_cmp_eq_u32 s5, 0
	s_cbranch_scc1 .LBB0_630
	v_readfirstlane_b32 s5, v22
	s_lshl_b32 s30, -2, s4
	s_and_b32 s5, s5, s30
	s_cbranch_execnz .LBB0_577

; #define LDS_WAIT() asm volatile("s_waitcnt lgkmcnt(0)" ::: "memory")
; __device__ __forceinline__ int lane_id() { int l; asm volatile("v_mbcnt_lo_u32_b32 %0, -1, 0\n\tv_mbcnt_hi_u32_b32 %0, -1, %0\n\ts_nop 1" : "=v"(l)); return l; }
; __device__ __forceinline__ unsigned f2ord(float f) { const unsigned u = __float_as_uint(f); return u ^ ((u >> 31) ? 0xFFFFFFFFu : 0x80000000u); }
; __device__ __forceinline__ int topk_compact(LAS u32x2* buf, int cnt, float& tau) {
;     const int lane = lane_id();
;     LDS_WAIT();
;     unsigned key[12], idx[12];
;     unsigned kmin = 0xFFFFFFFFu, kmax = 0u;
; #pragma unroll
;     for (int j = 0; j < 12; ++j) { const int e = j * 64 + lane; const u32x2 v = buf[e]; const bool ok = e < cnt; const unsigned k = f2ord(__uint_as_float(v.x)); key[j] = ok ? k : 0u; idx[j] = v.y;
;         kmin = (ok && k < kmin) ? k : kmin; kmax = (ok && k > kmax) ? k : kmax; }
; #pragma unroll
;     for (int o = 1; o < 64; o <<= 1) { const unsigned a = (unsigned)__shfl_xor((int)kmin, o), b = (unsigned)__shfl_xor((int)kmax, o); kmin = a < kmin ? a : kmin; kmax = b > kmax ? b : kmax; }
;     const unsigned diff = (unsigned)__builtin_amdgcn_readfirstlane((int)(kmin ^ kmax));
;     int bit = diff ? (31 - __builtin_clz(diff)) : -1;
;     unsigned T = (bit >= 0) ? (unsigned)__builtin_amdgcn_readfirstlane((int)kmin) & ~((2u << bit) - 1u) : (unsigned)__builtin_amdgcn_readfirstlane((int)kmin);
.LBB0_659:
	s_cmpk_lt_i32 s75, 0x101
	s_cbranch_scc1 .LBB0_745
	v_mbcnt_lo_u32_b32 v25, -1, 0
	v_mbcnt_hi_u32_b32 v25, -1, v25
	s_nop 1
	s_waitcnt lgkmcnt(0)
	s_waitcnt vmcnt(0)
	v_lshl_add_u32 v0, v25, 3, s97
	ds_read2st64_b64 v[20:23], v0 offset0:12 offset1:13
	ds_read2st64_b64 v[8:11], v0 offset0:14 offset1:15
	v_add_u32_e32 v2, 64, v25
	v_cmp_gt_i32_e64 s[6:7], s75, v2
	ds_read2st64_b64 v[16:19], v0 offset0:16 offset1:17
	ds_read2st64_b64 v[12:15], v0 offset0:18 offset1:19
	s_waitcnt lgkmcnt(3)
	v_cmp_lt_i32_e32 vcc, -1, v20
	v_add_u32_e32 v27, 0x200, v25
	v_cmp_gt_i32_e64 s[20:21], s75, v27
	v_cndmask_b32_e32 v1, -1, v123, vcc
	v_xor_b32_e32 v1, v1, v20
	v_cmp_gt_i32_e32 vcc, s75, v25
	s_nop 1
	v_cndmask_b32_e32 v24, 0, v1, vcc
	v_cndmask_b32_e32 v1, -1, v1, vcc
	v_cmp_lt_i32_e32 vcc, -1, v22
	s_nop 1
	v_cndmask_b32_e32 v3, -1, v123, vcc
	v_xor_b32_e32 v20, v3, v22
	s_waitcnt lgkmcnt(2)
	v_cmp_lt_i32_e32 vcc, -1, v8
	v_min_u32_e32 v3, v20, v1
	v_cndmask_b32_e64 v1, v1, v3, s[6:7]
	v_cndmask_b32_e32 v4, -1, v123, vcc
	v_max_u32_e32 v2, v20, v24
	v_add_u32_e32 v3, 0x80, v25
	v_xor_b32_e32 v8, v4, v8
	v_cndmask_b32_e64 v2, v24, v2, s[6:7]
	v_min_u32_e32 v4, v8, v1
	v_cmp_gt_i32_e64 s[8:9], s75, v3
	v_cmp_lt_i32_e32 vcc, -1, v10
	v_max_u32_e32 v3, v8, v2
	v_cndmask_b32_e64 v1, v1, v4, s[8:9]
	v_cndmask_b32_e32 v4, -1, v123, vcc
	v_cndmask_b32_e64 v2, v2, v3, s[8:9]
	v_add_u32_e32 v3, 0xc0, v25
	v_xor_b32_e32 v10, v4, v10
	v_min_u32_e32 v4, v10, v1
	v_cmp_gt_i32_e64 s[10:11], s75, v3
	s_waitcnt lgkmcnt(1)
	v_cmp_lt_i32_e32 vcc, -1, v16
	v_max_u32_e32 v3, v10, v2
	v_cndmask_b32_e64 v1, v1, v4, s[10:11]
	v_cndmask_b32_e32 v4, -1, v123, vcc
	v_cndmask_b32_e64 v2, v2, v3, s[10:11]
	v_add_u32_e32 v3, 0x100, v25
	v_xor_b32_e32 v16, v4, v16
	v_min_u32_e32 v4, v16, v1
	v_cmp_gt_i32_e64 s[12:13], s75, v3
	v_cmp_lt_i32_e32 vcc, -1, v18
	v_max_u32_e32 v3, v16, v2
	v_cndmask_b32_e64 v1, v1, v4, s[12:13]
	v_cndmask_b32_e32 v4, -1, v123, vcc
	v_cndmask_b32_e64 v2, v2, v3, s[12:13]
	v_add_u32_e32 v3, 0x140, v25
	v_xor_b32_e32 v18, v4, v18
	v_min_u32_e32 v4, v18, v1
	v_cmp_gt_i32_e64 s[14:15], s75, v3
	s_waitcnt lgkmcnt(0)
	v_cmp_lt_i32_e32 vcc, -1, v12
	v_max_u32_e32 v3, v18, v2
	v_cndmask_b32_e64 v1, v1, v4, s[14:15]
	v_cndmask_b32_e32 v4, -1, v123, vcc
	v_cndmask_b32_e64 v2, v2, v3, s[14:15]
	v_add_u32_e32 v3, 0x180, v25
	v_xor_b32_e32 v12, v4, v12
	v_min_u32_e32 v4, v12, v1
	v_cmp_gt_i32_e64 s[16:17], s75, v3
	v_cmp_lt_i32_e32 vcc, -1, v14
	v_max_u32_e32 v3, v12, v2
	v_cndmask_b32_e64 v1, v1, v4, s[16:17]
	v_cndmask_b32_e32 v4, -1, v123, vcc
	v_cndmask_b32_e64 v2, v2, v3, s[16:17]
	v_add_u32_e32 v3, 0x1c0, v25
	v_xor_b32_e32 v14, v4, v14
	v_min_u32_e32 v4, v14, v1
	v_cmp_gt_i32_e64 s[18:19], s75, v3
	s_nop 1
	v_cndmask_b32_e64 v22, v1, v4, s[18:19]
	ds_read2st64_b64 v[4:7], v0 offset0:20 offset1:21
	v_max_u32_e32 v1, v14, v2
	v_cndmask_b32_e64 v26, v2, v1, s[18:19]
	ds_read2st64_b64 v[0:3], v0 offset0:22 offset1:23
	s_waitcnt lgkmcnt(1)
	v_cmp_lt_i32_e32 vcc, -1, v4
	s_nop 1
	v_cndmask_b32_e32 v28, -1, v123, vcc
	v_xor_b32_e32 v4, v28, v4
	v_min_u32_e32 v28, v4, v22
	v_cmp_lt_i32_e32 vcc, -1, v6
	v_cndmask_b32_e64 v22, v22, v28, s[20:21]
	v_max_u32_e32 v27, v4, v26
	v_cndmask_b32_e32 v28, -1, v123, vcc
	v_cndmask_b32_e64 v26, v26, v27, s[20:21]
	v_add_u32_e32 v27, 0x240, v25
	v_xor_b32_e32 v6, v28, v6
	v_min_u32_e32 v28, v6, v22
	v_cmp_gt_i32_e64 s[22:23], s75, v27
	s_waitcnt lgkmcnt(0)
	v_cmp_lt_i32_e32 vcc, -1, v0
	v_max_u32_e32 v27, v6, v26
	v_cndmask_b32_e64 v22, v22, v28, s[22:23]
	v_cndmask_b32_e32 v28, -1, v123, vcc
	v_cndmask_b32_e64 v26, v26, v27, s[22:23]
	v_add_u32_e32 v27, 0x280, v25
	v_xor_b32_e32 v0, v28, v0
	v_cmp_gt_i32_e64 s[24:25], s75, v27
	v_max_u32_e32 v27, v0, v26
	v_cmp_lt_i32_e32 vcc, -1, v2
	v_cndmask_b32_e64 v26, v26, v27, s[24:25]
	v_min_u32_e32 v28, v0, v22
	v_cndmask_b32_e32 v27, -1, v123, vcc
	v_add_u32_e32 v25, 0x2c0, v25
	v_xor_b32_e32 v2, v27, v2
	v_cndmask_b32_e64 v22, v22, v28, s[24:25]
	v_cmp_gt_i32_e64 s[26:27], s75, v25
	v_max_u32_e32 v25, v2, v26
	v_min_u32_e32 v27, v2, v22
	v_cndmask_b32_e64 v25, v26, v25, s[26:27]
	v_and_b32_e32 v26, 64, v144
	v_cndmask_b32_e64 v22, v22, v27, s[26:27]
	v_add_u32_e32 v26, 64, v26
	s_nop 1
	v_min_u32_dpp v22, v22, v22 row_shr:1 row_mask:0xf bank_mask:0xf
	v_max_u32_dpp v25, v25, v25 row_shr:1 row_mask:0xf bank_mask:0xf
	s_nop 0
	v_min_u32_dpp v22, v22, v22 row_shr:2 row_mask:0xf bank_mask:0xf
	v_max_u32_dpp v25, v25, v25 row_shr:2 row_mask:0xf bank_mask:0xf
	s_nop 0
	v_min_u32_dpp v22, v22, v22 row_shr:4 row_mask:0xf bank_mask:0xf
	v_max_u32_dpp v25, v25, v25 row_shr:4 row_mask:0xf bank_mask:0xf
	s_nop 0
	v_min_u32_dpp v22, v22, v22 row_shr:8 row_mask:0xf bank_mask:0xf
	v_max_u32_dpp v25, v25, v25 row_shr:8 row_mask:0xf bank_mask:0xf
	s_nop 0
	v_readlane_b32 s4, v22, 15
	v_readlane_b32 s5, v22, 31
	s_min_u32 s4, s4, s5
	v_readlane_b32 s5, v22, 47
	s_min_u32 s4, s4, s5
	v_readlane_b32 s5, v22, 63
	s_min_u32 s4, s4, s5
	v_mov_b32_e32 v22, s4
	v_readlane_b32 s4, v25, 15
	v_readlane_b32 s5, v25, 31
	s_max_u32 s4, s4, s5
	v_readlane_b32 s5, v25, 47
	s_max_u32 s4, s4, s5
	v_readlane_b32 s5, v25, 63
	s_max_u32 s4, s4, s5
	v_mov_b32_e32 v25, s4
	s_branch .Lpad_kmm8648
	s_nop 0
	s_nop 0
	s_nop 0
	s_nop 0
	s_nop 0
	s_nop 0
	s_nop 0
	s_nop 0
	s_nop 0
	s_nop 0
	s_nop 0
	s_nop 0
	s_nop 0
	s_nop 0
	s_nop 0
	s_nop 0
	s_nop 0
	s_nop 0
	s_nop 0
	s_nop 0
	s_nop 0
	s_nop 0
	s_nop 0
	s_nop 0
	s_nop 0
	s_nop 0
	s_nop 0
	s_nop 0
	s_nop 0
	s_nop 0
	s_nop 0
	s_nop 0
